# grid barrier: non-leader workgroups poll the top-level generation word directly instead of their XCD release word (one hop less)
# speedup vs baseline: 1.0028x; 1.0021x over previous
.LBB0_119:
	s_lshl_b32 s6, s68, 8
	s_add_u32 s6, s28, s6
	s_addc_u32 s7, s29, 0
	v_mov_b32_e32 v1, 0x1000
	v_mov_b32_e32 v3, 1
	global_atomic_add v3, v1, v3, s[6:7] offset:1024 sc0
	v_cvt_f32_u32_e32 v1, v2
	v_sub_u32_e32 v4, 0, v2
	v_rcp_iflag_f32_e32 v1, v1
	s_nop 0
	v_mul_f32_e32 v1, 0x4f7ffffe, v1
	v_cvt_u32_f32_e32 v1, v1
	v_mul_lo_u32 v4, v4, v1
	v_mul_hi_u32 v4, v1, v4
	v_add_u32_e32 v1, v1, v4
	s_waitcnt vmcnt(0)
	v_mul_hi_u32 v1, v3, v1
	v_mul_lo_u32 v4, v1, v2
	v_sub_u32_e32 v4, v3, v4
	v_add_u32_e32 v5, 1, v1
	v_cmp_ge_u32_e32 vcc, v4, v2
	v_add_u32_e32 v3, 1, v3
	s_nop 0
	v_cndmask_b32_e32 v1, v1, v5, vcc
	v_sub_u32_e32 v5, v4, v2
	v_cndmask_b32_e32 v4, v4, v5, vcc
	v_add_u32_e32 v5, 1, v1
	v_cmp_ge_u32_e32 vcc, v4, v2
	s_nop 1
	v_cndmask_b32_e32 v1, v1, v5, vcc
	v_mul_lo_u32 v4, v2, v1
	v_add_u32_e32 v2, v4, v2
	v_cmp_ne_u32_e32 vcc, v3, v2
	s_and_saveexec_b64 s[8:9], vcc
	s_xor_b64 s[8:9], exec, s[8:9]
	s_cbranch_execz .LBB0_133
	s_waitcnt lgkmcnt(0)
	v_mov_b32_e32 v0, 0x3500
	global_load_dword v0, v0, s[28:29] sc1
	s_add_u32 s12, s28, 0x3500
	s_addc_u32 s13, s29, 0
	s_waitcnt vmcnt(0)
	v_cmp_eq_u32_e32 vcc, v0, v1
	s_and_saveexec_b64 s[10:11], vcc
	s_cbranch_execz .LBB0_132
	s_mov_b32 s14, 1
	s_mov_b64 s[38:39], 0
	v_mov_b32_e32 v0, 0
	s_branch .LBB0_123

.LBB0_254:
	s_lshl_b32 s4, s68, 8
	s_add_u32 s4, s28, s4
	s_addc_u32 s5, s29, 0
	v_mov_b32_e32 v1, 0x1000
	v_mov_b32_e32 v3, 1
	global_atomic_add v3, v1, v3, s[4:5] offset:1024 sc0
	v_cvt_f32_u32_e32 v1, v2
	v_sub_u32_e32 v4, 0, v2
	v_rcp_iflag_f32_e32 v1, v1
	s_nop 0
	v_mul_f32_e32 v1, 0x4f7ffffe, v1
	v_cvt_u32_f32_e32 v1, v1
	v_mul_lo_u32 v4, v4, v1
	v_mul_hi_u32 v4, v1, v4
	v_add_u32_e32 v1, v1, v4
	s_waitcnt vmcnt(0)
	v_mul_hi_u32 v1, v3, v1
	v_mul_lo_u32 v4, v1, v2
	v_sub_u32_e32 v4, v3, v4
	v_add_u32_e32 v5, 1, v1
	v_cmp_ge_u32_e32 vcc, v4, v2
	v_add_u32_e32 v3, 1, v3
	s_nop 0
	v_cndmask_b32_e32 v1, v1, v5, vcc
	v_sub_u32_e32 v5, v4, v2
	v_cndmask_b32_e32 v4, v4, v5, vcc
	v_add_u32_e32 v5, 1, v1
	v_cmp_ge_u32_e32 vcc, v4, v2
	s_nop 1
	v_cndmask_b32_e32 v1, v1, v5, vcc
	v_mul_lo_u32 v4, v2, v1
	v_add_u32_e32 v2, v4, v2
	v_cmp_ne_u32_e32 vcc, v3, v2
	s_and_saveexec_b64 s[6:7], vcc
	s_xor_b64 s[6:7], exec, s[6:7]
	s_cbranch_execz .LBB0_268
	s_waitcnt lgkmcnt(0)
	v_mov_b32_e32 v0, 0x3500
	global_load_dword v0, v0, s[28:29] sc1
	s_add_u32 s10, s28, 0x3500
	s_addc_u32 s11, s29, 0
	s_waitcnt vmcnt(0)
	v_cmp_eq_u32_e32 vcc, v0, v1
	s_and_saveexec_b64 s[8:9], vcc
	s_cbranch_execz .LBB0_267
	s_mov_b32 s14, 1
	s_mov_b64 s[12:13], 0
	v_mov_b32_e32 v0, 0
	s_branch .LBB0_258

.LBB0_551:
	s_lshl_b32 s4, s68, 8
	s_add_u32 s4, s28, s4
	s_addc_u32 s5, s29, 0
	v_mov_b32_e32 v1, 0x1000
	v_mov_b32_e32 v3, 1
	global_atomic_add v3, v1, v3, s[4:5] offset:1024 sc0
	v_cvt_f32_u32_e32 v1, v2
	v_sub_u32_e32 v4, 0, v2
	v_rcp_iflag_f32_e32 v1, v1
	s_nop 0
	v_mul_f32_e32 v1, 0x4f7ffffe, v1
	v_cvt_u32_f32_e32 v1, v1
	v_mul_lo_u32 v4, v4, v1
	v_mul_hi_u32 v4, v1, v4
	v_add_u32_e32 v1, v1, v4
	s_waitcnt vmcnt(0)
	v_mul_hi_u32 v1, v3, v1
	v_mul_lo_u32 v4, v1, v2
	v_sub_u32_e32 v4, v3, v4
	v_add_u32_e32 v5, 1, v1
	v_cmp_ge_u32_e32 vcc, v4, v2
	v_add_u32_e32 v3, 1, v3
	s_nop 0
	v_cndmask_b32_e32 v1, v1, v5, vcc
	v_sub_u32_e32 v5, v4, v2
	v_cndmask_b32_e32 v4, v4, v5, vcc
	v_add_u32_e32 v5, 1, v1
	v_cmp_ge_u32_e32 vcc, v4, v2
	s_nop 1
	v_cndmask_b32_e32 v1, v1, v5, vcc
	v_mul_lo_u32 v4, v2, v1
	v_add_u32_e32 v2, v4, v2
	v_cmp_ne_u32_e32 vcc, v3, v2
	s_and_saveexec_b64 s[8:9], vcc
	s_xor_b64 s[8:9], exec, s[8:9]
	s_cbranch_execz .LBB0_565
	s_waitcnt lgkmcnt(0)
	v_mov_b32_e32 v0, 0x3500
	global_load_dword v0, v0, s[28:29] sc1
	s_add_u32 s12, s28, 0x3500
	s_addc_u32 s13, s29, 0
	s_waitcnt vmcnt(0)
	v_cmp_eq_u32_e32 vcc, v0, v1
	s_and_saveexec_b64 s[10:11], vcc
	s_cbranch_execz .LBB0_564
	s_mov_b32 s18, 1
	s_mov_b64 s[14:15], 0
	v_mov_b32_e32 v0, 0
	s_branch .LBB0_555

.LBB0_642:
	s_lshl_b32 s6, s68, 8
	s_add_u32 s6, s28, s6
	s_addc_u32 s7, s29, 0
	v_mov_b32_e32 v1, 0x1000
	v_mov_b32_e32 v3, 1
	global_atomic_add v3, v1, v3, s[6:7] offset:1024 sc0
	v_cvt_f32_u32_e32 v1, v2
	v_sub_u32_e32 v4, 0, v2
	v_rcp_iflag_f32_e32 v1, v1
	s_nop 0
	v_mul_f32_e32 v1, 0x4f7ffffe, v1
	v_cvt_u32_f32_e32 v1, v1
	v_mul_lo_u32 v4, v4, v1
	v_mul_hi_u32 v4, v1, v4
	v_add_u32_e32 v1, v1, v4
	s_waitcnt vmcnt(0)
	v_mul_hi_u32 v1, v3, v1
	v_mul_lo_u32 v4, v1, v2
	v_sub_u32_e32 v4, v3, v4
	v_add_u32_e32 v5, 1, v1
	v_cmp_ge_u32_e32 vcc, v4, v2
	v_add_u32_e32 v3, 1, v3
	s_nop 0
	v_cndmask_b32_e32 v1, v1, v5, vcc
	v_sub_u32_e32 v5, v4, v2
	v_cndmask_b32_e32 v4, v4, v5, vcc
	v_add_u32_e32 v5, 1, v1
	v_cmp_ge_u32_e32 vcc, v4, v2
	s_nop 1
	v_cndmask_b32_e32 v1, v1, v5, vcc
	v_mul_lo_u32 v4, v2, v1
	v_add_u32_e32 v2, v4, v2
	v_cmp_ne_u32_e32 vcc, v3, v2
	s_and_saveexec_b64 s[10:11], vcc
	s_xor_b64 s[10:11], exec, s[10:11]
	s_cbranch_execz .LBB0_656
	s_waitcnt lgkmcnt(0)
	v_mov_b32_e32 v0, 0x3500
	global_load_dword v0, v0, s[28:29] sc1
	s_add_u32 s14, s28, 0x3500
	s_addc_u32 s15, s29, 0
	s_waitcnt vmcnt(0)
	v_cmp_eq_u32_e32 vcc, v0, v1
	s_and_saveexec_b64 s[12:13], vcc
	s_cbranch_execz .LBB0_655
	s_mov_b32 s18, 1
	s_mov_b64 s[20:21], 0
	v_mov_b32_e32 v0, 0
	s_branch .LBB0_646

.LBB0_711:
	s_lshl_b32 s6, s68, 8
	s_add_u32 s6, s28, s6
	s_addc_u32 s7, s29, 0
	v_mov_b32_e32 v1, 0x1000
	v_mov_b32_e32 v3, 1
	global_atomic_add v3, v1, v3, s[6:7] offset:1024 sc0
	v_cvt_f32_u32_e32 v1, v2
	v_sub_u32_e32 v4, 0, v2
	v_rcp_iflag_f32_e32 v1, v1
	s_nop 0
	v_mul_f32_e32 v1, 0x4f7ffffe, v1
	v_cvt_u32_f32_e32 v1, v1
	v_mul_lo_u32 v4, v4, v1
	v_mul_hi_u32 v4, v1, v4
	v_add_u32_e32 v1, v1, v4
	s_waitcnt vmcnt(0)
	v_mul_hi_u32 v1, v3, v1
	v_mul_lo_u32 v4, v1, v2
	v_sub_u32_e32 v4, v3, v4
	v_add_u32_e32 v5, 1, v1
	v_cmp_ge_u32_e32 vcc, v4, v2
	v_add_u32_e32 v3, 1, v3
	s_nop 0
	v_cndmask_b32_e32 v1, v1, v5, vcc
	v_sub_u32_e32 v5, v4, v2
	v_cndmask_b32_e32 v4, v4, v5, vcc
	v_add_u32_e32 v5, 1, v1
	v_cmp_ge_u32_e32 vcc, v4, v2
	s_nop 1
	v_cndmask_b32_e32 v1, v1, v5, vcc
	v_mul_lo_u32 v4, v2, v1
	v_add_u32_e32 v2, v4, v2
	v_cmp_ne_u32_e32 vcc, v3, v2
	s_and_saveexec_b64 s[8:9], vcc
	s_xor_b64 s[8:9], exec, s[8:9]
	s_cbranch_execz .LBB0_725
	s_waitcnt lgkmcnt(0)
	v_mov_b32_e32 v0, 0x3500
	global_load_dword v0, v0, s[28:29] sc1
	s_add_u32 s12, s28, 0x3500
	s_addc_u32 s13, s29, 0
	s_waitcnt vmcnt(0)
	v_cmp_eq_u32_e32 vcc, v0, v1
	s_and_saveexec_b64 s[10:11], vcc
	s_cbranch_execz .LBB0_724
	s_mov_b32 s18, 1
	s_mov_b64 s[14:15], 0
	v_mov_b32_e32 v0, 0
	s_branch .LBB0_715
